# grid barrier: the first workgroup of each XCD to arrive starts an L2 write-back early (buffer_wbl2 sc1) in the shadow of the workgroups still working
# baseline (speedup 1.0000x reference)
; __device__ __forceinline__ unsigned xb_ld(unsigned* p)              { return __hip_atomic_load(p, __ATOMIC_RELAXED, __HIP_MEMORY_SCOPE_AGENT); }
; __device__ __forceinline__ unsigned xb_add(unsigned* p, unsigned v) { return __hip_atomic_fetch_add(p, v, __ATOMIC_RELAXED, __HIP_MEMORY_SCOPE_AGENT); }
; #define XB_SPIN(cond, bar) do { unsigned _sp = 0; while (cond) { __builtin_amdgcn_s_sleep(1); \
;     if ((++_sp & 255u) == 0u) { if (xb_ld(&(bar)[XB_TMO])) break; if (_sp > XB_SPIN_CAP) { atomicAdd(&(bar)[XB_TMO], 1u); break; } } } } while (0)
; __device__ __forceinline__ void xcd_barrier(const XcdBarrier& b, int tid) {
;     ...
;         const unsigned old = xb_add(&bar[XB_XSUB(b.x)], 1u);
;         const unsigned gen = old / nloc;
;         if (old + 1u == (gen + 1u) * nloc) {
;             __builtin_amdgcn_fence(__ATOMIC_RELEASE, "agent");
;             asm volatile("s_waitcnt vmcnt(0)" ::: "memory");
;             const unsigned og = xb_add(&bar[XB_TOP], 1u);
;             const unsigned tg = og / nx;
;             if (og + 1u == (tg + 1u) * nx) xb_add(&bar[XB_TOPGEN], 1u);
;             else XB_SPIN(xb_ld(&bar[XB_TOPGEN]) == tg, bar);
;             __builtin_amdgcn_fence(__ATOMIC_ACQUIRE, "agent");
;             xb_add(&bar[XB_XGEN(b.x)], 1u);
;             asm volatile("s_waitcnt vmcnt(0)" ::: "memory");
;         } else {
;             XB_SPIN(xb_ld(&bar[XB_XGEN(b.x)]) == gen, bar);
.LBB0_838:
	s_or_b64 exec, exec, s[2:3]
	v_cvt_f32_u32_e32 v5, v3
	s_waitcnt vmcnt(0)
	v_readfirstlane_b32 s2, v4
	v_sub_u32_e32 v4, 0, v3
	v_rcp_iflag_f32_e32 v5, v5
	v_add_u32_e32 v6, s2, v0
	v_mul_f32_e32 v5, 0x4f7ffffe, v5
	v_cvt_u32_f32_e32 v5, v5
	v_mul_lo_u32 v0, v4, v5
	v_mul_hi_u32 v0, v5, v0
	v_add_u32_e32 v0, v5, v0
	v_mul_hi_u32 v0, v6, v0
	v_mul_lo_u32 v4, v0, v3
	v_sub_u32_e32 v4, v6, v4
	v_add_u32_e32 v5, 1, v0
	v_cmp_ge_u32_e32 vcc, v4, v3
	s_nop 1
	v_cndmask_b32_e32 v0, v0, v5, vcc
	v_sub_u32_e32 v5, v4, v3
	v_cndmask_b32_e32 v4, v4, v5, vcc
	v_add_u32_e32 v5, 1, v0
	v_cmp_ge_u32_e32 vcc, v4, v3
	v_add_u32_e32 v4, 1, v6
	s_nop 0
	v_cndmask_b32_e32 v0, v0, v5, vcc
	v_mul_lo_u32 v5, v3, v0
	v_cmp_eq_u32_e32 vcc, v6, v5
	s_and_b64 vcc, exec, vcc
	s_cbranch_vccz .Lbar_nofirst
	buffer_wbl2 sc1
.Lbar_nofirst:
	v_add_u32_e32 v3, v5, v3
	v_cmp_ne_u32_e32 vcc, v4, v3
	s_and_saveexec_b64 s[2:3], vcc
	s_xor_b64 s[2:3], exec, s[2:3]
	s_cbranch_execz .LBB0_852
	v_readlane_b32 s4, v253, 18
	v_readlane_b32 s5, v253, 19
	s_waitcnt lgkmcnt(0)
	s_nop 3
	global_load_dword v2, v1, s[4:5] sc1
	s_waitcnt vmcnt(0)
	v_cmp_eq_u32_e32 vcc, v2, v0
	s_and_saveexec_b64 s[4:5], vcc
	s_cbranch_execz .LBB0_851
	s_mov_b32 s8, 1
	s_mov_b64 s[6:7], 0
	s_branch .LBB0_842
